# retention staging: q,k,v loads issued together (was three dependent round trips)
# baseline (speedup 1.0000x reference)
; #define LAS __attribute__((address_space(3)))
; __device__ __forceinline__ void ret_stage(const Frame& F, int b, int h, int n, bool full, float lg) {
;     LAS unsigned char* L = F.lds;
;     const int tk = F.tid >> 2, part = F.tid & 3;
;     const size_t rowoff = (((size_t)b * 4 + h) * S + n * 128 + tk) * 64 + part * 16;
;     const u32x4* kp = (const u32x4*)((const bf16*)(F.ws + WS_PRK) + rowoff);
;     const u32x4* vp = (const u32x4*)((const bf16*)(F.ws + WS_PRV) + rowoff);
;     const u32x4 k0 = kp[0], k1 = kp[1], v0 = vp[0], v1 = vp[1];
;     if (full) { const u32x4* qp = (const u32x4*)((const bf16*)(F.ws + WS_PRQ) + rowoff);
;         const u32x4 q0 = qp[0], q1 = qp[1];
;         *(LAS u32x4*)(L + RL_Q + tk * 128 + part * 32) = q0; *(LAS u32x4*)(L + RL_Q + tk * 128 + part * 32 + 16) = q1;
;         *(LAS u32x4*)(L + RL_K + tk * 128 + part * 32) = k0; *(LAS u32x4*)(L + RL_K + tk * 128 + part * 32 + 16) = k1; }
;     const float kd = expf((float)(127 - tk) * lg);
;     const unsigned kw[8] = {k0.x, k0.y, k0.z, k0.w, k1.x, k1.y, k1.z, k1.w}, vw[8] = {v0.x, v0.y, v0.z, v0.w, v1.x, v1.y, v1.z, v1.w};
; #pragma unroll
;     for (int i = 0; i < 8; ++i) { const int d = part * 16 + 2 * i;
;         if (!full) { const unsigned pk = cvt_pk_bf16(bf2f((unsigned short)(kw[i] & 0xffffu)) * kd, bf2f((unsigned short)(kw[i] >> 16)) * kd);
;             *(LAS unsigned short*)(L + RL_KT + (d * 128 + tk) * 2) = (unsigned short)(pk & 0xffffu); *(LAS unsigned short*)(L + RL_KT + ((d + 1) * 128 + tk) * 2) = (unsigned short)(pk >> 16); }
;         *(LAS unsigned short*)(L + RL_VT + (d * 128 + tk) * 2) = (unsigned short)(vw[i] & 0xffffu); *(LAS unsigned short*)(L + RL_VT + ((d + 1) * 128 + tk) * 2) = (unsigned short)(vw[i] >> 16); }
; __device__ __forceinline__ void ret_out_unit(const Frame& F, int l, int unit) {
;     const int n = unit & 15, h = (unit >> 4) & 3, b = unit >> 6;
;     const float lg = c_log_gamma[h];
;     LAS unsigned char* L = F.lds;
;     __syncthreads();
;     ret_stage(F, b, h, n, true, lg);
;     {
;         const int idx8 = F.tid * 8, d = idx8 >> 6, e0 = idx8 & 63;
;         f32x4 s0 = {0.f, 0.f, 0.f, 0.f}, s1 = {0.f, 0.f, 0.f, 0.f};
;         const float* kvb = (const float*)(F.ws + WS_KVB) + (((size_t)b * 4 + h) * 16) * 4096 + idx8;
; #pragma unroll
;         for (int mb = 0; mb < 16; mb += 8) {
;             f32x4 t0[8], t1[8];
; #pragma unroll
.LBB0_1560:
	s_bfe_u32 s79, s77, 0x20004
	s_and_b32 s3, s77, 15
	s_ashr_i32 s72, s77, 6
	s_lshl_b32 s26, s79, 2
	s_getpc_b64 s[10:11]
	s_add_u32 s10, s10, c_log_gamma@rel32@lo+4
	s_addc_u32 s11, s11, c_log_gamma@rel32@hi+12
	s_load_dword s78, s[10:11], s26 offset:0x0
	s_ashr_i32 s73, s72, 31
	s_lshl_b32 s26, s79, 11
	s_lshl_b32 s34, s3, 7
	s_lshl_b64 s[10:11], s[72:73], 13
	s_or_b32 s26, s26, s34
	s_or_b32 s10, s10, s26
	v_lshl_add_u64 v[2:3], s[10:11], 0, v[122:123]
	v_lshlrev_b64 v[10:11], 7, v[2:3]
	v_lshl_or_b32 v10, v124, 1, v10
	v_lshl_add_u64 v[6:7], s[14:15], 0, v[10:11]
	v_lshl_add_u64 v[14:15], s[36:37], 0, v[10:11]
	s_waitcnt lgkmcnt(0)
	s_barrier
	v_lshl_add_u64 v[18:19], s[28:29], 0, v[10:11]
	global_load_dwordx4 v[2:5], v[6:7], off offset:16
	s_nop 0
	global_load_dwordx4 v[6:9], v[6:7], off
	s_nop 0
	global_load_dwordx4 v[10:13], v[14:15], off offset:16
	s_nop 0
	global_load_dwordx4 v[14:17], v[14:15], off
	global_load_dwordx4 v[26:29], v[18:19], off
	global_load_dwordx4 v[30:33], v[18:19], off offset:16
	s_lshl_b64 s[10:11], s[72:73], 20
	s_add_u32 s10, s4, s10
	s_addc_u32 s11, s5, s11
	s_lshl_b32 s26, s79, 18
	s_add_u32 s10, s10, s26
	s_addc_u32 s11, s11, 0
	s_cmp_eq_u32 s3, 0
	s_cselect_b64 s[26:27], -1, 0
	v_lshl_add_u64 v[140:141], v[126:127], 2, s[10:11]
	s_and_b64 vcc, exec, s[26:27]
	v_mov_b32_e32 v22, 0
	v_mov_b32_e32 v23, 0
	v_mov_b32_e32 v24, 0
	v_mov_b32_e32 v25, 0
	s_waitcnt vmcnt(2)
	ds_write_b128 v154, v[14:17]
	ds_write_b128 v154, v[10:13] offset:16
	ds_write_b128 v154, v[6:9] offset:16384
	ds_write_b128 v154, v[2:5] offset:16400
	v_mov_b32_e32 v14, 0
	v_mov_b32_e32 v15, 0
	v_mov_b32_e32 v16, 0
	v_mov_b32_e32 v17, 0
	s_waitcnt vmcnt(1)
	ds_write_b16 v155, v26 offset:49152
	ds_write_b16_d16_hi v156, v26 offset:49408
	ds_write_b16 v155, v27 offset:49664
	ds_write_b16_d16_hi v156, v27 offset:49920
	ds_write_b16 v155, v28 offset:50176
	ds_write_b16_d16_hi v156, v28 offset:50432
	ds_write_b16 v155, v29 offset:50688
	ds_write_b16_d16_hi v156, v29 offset:50944
	s_waitcnt vmcnt(0)
	ds_write_b16 v155, v30 offset:51200
	ds_write_b16_d16_hi v156, v30 offset:51456
	ds_write_b16 v155, v31 offset:51712
	ds_write_b16_d16_hi v156, v31 offset:51968
	ds_write_b16 v155, v32 offset:52224
	ds_write_b16_d16_hi v156, v32 offset:52480
	ds_write_b16 v155, v33 offset:52736
	ds_write_b16_d16_hi v156, v33 offset:52992
	v_mov_b32_e32 v2, 0
	s_cbranch_vccnz .LBB0_1562
	global_load_dwordx4 v[14:17], v[140:141], off
	global_load_dwordx4 v[22:25], v[140:141], off offset:16
